# grid barrier, non-leader workgroups: acquire-side buffer_inv sc1 issued at arrival (before polling the XCD release word) instead of after the release is seen; polls are L1-bypassing and all other wave
# speedup vs baseline: 1.0102x; 1.0102x over previous
.LBB0_91:
	s_or_b64 exec, exec, s[8:9]
	v_cvt_f32_u32_e32 v4, v2
	s_waitcnt vmcnt(0)
	v_readfirstlane_b32 s4, v3
	v_sub_u32_e32 v3, 0, v2
	v_rcp_iflag_f32_e32 v4, v4
	v_add_u32_e32 v5, s4, v1
	v_mul_f32_e32 v4, 0x4f7ffffe, v4
	v_cvt_u32_f32_e32 v4, v4
	v_mul_lo_u32 v1, v3, v4
	v_mul_hi_u32 v1, v4, v1
	v_add_u32_e32 v1, v4, v1
	v_mul_hi_u32 v1, v5, v1
	v_mul_lo_u32 v3, v1, v2
	v_sub_u32_e32 v3, v5, v3
	v_add_u32_e32 v4, 1, v1
	v_cmp_ge_u32_e32 vcc, v3, v2
	s_nop 1
	v_cndmask_b32_e32 v1, v1, v4, vcc
	v_sub_u32_e32 v4, v3, v2
	v_cndmask_b32_e32 v3, v3, v4, vcc
	v_add_u32_e32 v4, 1, v1
	v_cmp_ge_u32_e32 vcc, v3, v2
	v_add_u32_e32 v3, 1, v5
	s_nop 0
	v_cndmask_b32_e32 v1, v1, v4, vcc
	v_mul_lo_u32 v4, v2, v1
	v_add_u32_e32 v2, v4, v2
	v_cmp_ne_u32_e32 vcc, v3, v2
	s_and_saveexec_b64 s[4:5], vcc
	s_xor_b64 s[4:5], exec, s[4:5]
	s_cbranch_execz .LBB0_105
	buffer_inv sc1
	s_waitcnt lgkmcnt(0)
	v_mov_b32_e32 v0, 0x2000
	global_load_dword v0, v0, s[0:1] offset:1024 sc1
	s_add_u32 s28, s0, 0x2400
	s_addc_u32 s29, s1, 0
	s_waitcnt vmcnt(0)
	v_cmp_eq_u32_e32 vcc, v0, v1
	s_and_saveexec_b64 s[8:9], vcc
	s_cbranch_execz .LBB0_104
	s_add_u32 s14, s72, 0x1fd00200
	s_addc_u32 s15, s73, 0
	s_mov_b32 s11, 1
	s_mov_b64 s[30:31], 0
	v_mov_b32_e32 v0, 0
	s_branch .LBB0_95

.LBB0_104:
	s_or_b64 exec, exec, s[8:9]
	s_waitcnt vmcnt(0)
	s_nop 0
	s_waitcnt vmcnt(0)

.LBB0_337:
	s_or_b64 exec, exec, s[8:9]
	v_cvt_f32_u32_e32 v4, v2
	s_waitcnt vmcnt(0)
	v_readfirstlane_b32 s6, v3
	v_sub_u32_e32 v3, 0, v2
	v_rcp_iflag_f32_e32 v4, v4
	v_add_u32_e32 v5, s6, v1
	v_mul_f32_e32 v4, 0x4f7ffffe, v4
	v_cvt_u32_f32_e32 v4, v4
	v_mul_lo_u32 v1, v3, v4
	v_mul_hi_u32 v1, v4, v1
	v_add_u32_e32 v1, v4, v1
	v_mul_hi_u32 v1, v5, v1
	v_mul_lo_u32 v3, v1, v2
	v_sub_u32_e32 v3, v5, v3
	v_add_u32_e32 v4, 1, v1
	v_cmp_ge_u32_e32 vcc, v3, v2
	s_nop 1
	v_cndmask_b32_e32 v1, v1, v4, vcc
	v_sub_u32_e32 v4, v3, v2
	v_cndmask_b32_e32 v3, v3, v4, vcc
	v_add_u32_e32 v4, 1, v1
	v_cmp_ge_u32_e32 vcc, v3, v2
	v_add_u32_e32 v3, 1, v5
	s_nop 0
	v_cndmask_b32_e32 v1, v1, v4, vcc
	v_mul_lo_u32 v4, v2, v1
	v_add_u32_e32 v2, v4, v2
	v_cmp_ne_u32_e32 vcc, v3, v2
	s_and_saveexec_b64 s[6:7], vcc
	s_xor_b64 s[6:7], exec, s[6:7]
	s_cbranch_execz .LBB0_351
	buffer_inv sc1
	s_waitcnt lgkmcnt(0)
	v_mov_b32_e32 v0, 0x2000
	global_load_dword v0, v0, s[4:5] offset:1024 sc1
	s_add_u32 s16, s4, 0x2400
	s_addc_u32 s17, s5, 0
	s_waitcnt vmcnt(0)
	v_cmp_eq_u32_e32 vcc, v0, v1
	s_and_saveexec_b64 s[8:9], vcc
	s_cbranch_execz .LBB0_350
	s_add_u32 s12, s72, 0x1fd00200
	s_addc_u32 s13, s73, 0
	s_mov_b32 s11, 1
	s_mov_b64 s[18:19], 0
	v_mov_b32_e32 v0, 0
	s_branch .LBB0_341

.LBB0_586:
	s_or_b64 exec, exec, s[12:13]
	v_cvt_f32_u32_e32 v4, v2
	s_waitcnt vmcnt(0)
	v_readfirstlane_b32 s8, v3
	v_sub_u32_e32 v3, 0, v2
	v_rcp_iflag_f32_e32 v4, v4
	v_add_u32_e32 v5, s8, v1
	v_mul_f32_e32 v4, 0x4f7ffffe, v4
	v_cvt_u32_f32_e32 v4, v4
	v_mul_lo_u32 v1, v3, v4
	v_mul_hi_u32 v1, v4, v1
	v_add_u32_e32 v1, v4, v1
	v_mul_hi_u32 v1, v5, v1
	v_mul_lo_u32 v3, v1, v2
	v_sub_u32_e32 v3, v5, v3
	v_add_u32_e32 v4, 1, v1
	v_cmp_ge_u32_e32 vcc, v3, v2
	s_nop 1
	v_cndmask_b32_e32 v1, v1, v4, vcc
	v_sub_u32_e32 v4, v3, v2
	v_cndmask_b32_e32 v3, v3, v4, vcc
	v_add_u32_e32 v4, 1, v1
	v_cmp_ge_u32_e32 vcc, v3, v2
	v_add_u32_e32 v3, 1, v5
	s_nop 0
	v_cndmask_b32_e32 v1, v1, v4, vcc
	v_mul_lo_u32 v4, v2, v1
	v_add_u32_e32 v2, v4, v2
	v_cmp_ne_u32_e32 vcc, v3, v2
	s_and_saveexec_b64 s[8:9], vcc
	s_xor_b64 s[8:9], exec, s[8:9]
	s_cbranch_execz .LBB0_600
	buffer_inv sc1
	s_waitcnt lgkmcnt(0)
	v_mov_b32_e32 v0, 0x2000
	global_load_dword v0, v0, s[4:5] offset:1024 sc1
	s_add_u32 s18, s4, 0x2400
	s_addc_u32 s19, s5, 0
	s_waitcnt vmcnt(0)
	v_cmp_eq_u32_e32 vcc, v0, v1
	s_and_saveexec_b64 s[12:13], vcc
	s_cbranch_execz .LBB0_599
	s_add_u32 s16, s72, 0x1fd00200
	s_addc_u32 s17, s73, 0
	s_mov_b32 s11, 1
	s_mov_b64 s[20:21], 0
	v_mov_b32_e32 v0, 0
	s_branch .LBB0_590

.LBB0_599:
	s_or_b64 exec, exec, s[12:13]
	s_waitcnt vmcnt(0)
	s_nop 0
	s_waitcnt vmcnt(0)

.LBB0_684:
	s_or_b64 exec, exec, s[16:17]
	v_cvt_f32_u32_e32 v4, v2
	s_waitcnt vmcnt(0)
	v_readfirstlane_b32 s8, v3
	v_sub_u32_e32 v3, 0, v2
	v_rcp_iflag_f32_e32 v4, v4
	v_add_u32_e32 v5, s8, v1
	v_mul_f32_e32 v4, 0x4f7ffffe, v4
	v_cvt_u32_f32_e32 v4, v4
	v_mul_lo_u32 v1, v3, v4
	v_mul_hi_u32 v1, v4, v1
	v_add_u32_e32 v1, v4, v1
	v_mul_hi_u32 v1, v5, v1
	v_mul_lo_u32 v3, v1, v2
	v_sub_u32_e32 v3, v5, v3
	v_add_u32_e32 v4, 1, v1
	v_cmp_ge_u32_e32 vcc, v3, v2
	s_nop 1
	v_cndmask_b32_e32 v1, v1, v4, vcc
	v_sub_u32_e32 v4, v3, v2
	v_cndmask_b32_e32 v3, v3, v4, vcc
	v_add_u32_e32 v4, 1, v1
	v_cmp_ge_u32_e32 vcc, v3, v2
	v_add_u32_e32 v3, 1, v5
	s_nop 0
	v_cndmask_b32_e32 v1, v1, v4, vcc
	v_mul_lo_u32 v4, v2, v1
	v_add_u32_e32 v2, v4, v2
	v_cmp_ne_u32_e32 vcc, v3, v2
	s_and_saveexec_b64 s[8:9], vcc
	s_xor_b64 s[8:9], exec, s[8:9]
	s_cbranch_execz .LBB0_698
	buffer_inv sc1
	s_waitcnt lgkmcnt(0)
	v_mov_b32_e32 v0, 0x2000
	global_load_dword v0, v0, s[4:5] offset:1024 sc1
	s_add_u32 s20, s4, 0x2400
	s_addc_u32 s21, s5, 0
	s_waitcnt vmcnt(0)
	v_cmp_eq_u32_e32 vcc, v0, v1
	s_and_saveexec_b64 s[16:17], vcc
	s_cbranch_execz .LBB0_697
	s_add_u32 s18, s72, 0x1fd00200
	s_addc_u32 s19, s73, 0
	s_mov_b32 s11, 1
	s_mov_b64 s[22:23], 0
	v_mov_b32_e32 v0, 0
	s_branch .LBB0_688

.LBB0_697:
	s_or_b64 exec, exec, s[16:17]
	s_waitcnt vmcnt(0)
	s_nop 0
	s_waitcnt vmcnt(0)

.LBB0_841:
	s_or_b64 exec, exec, s[8:9]
	v_cvt_f32_u32_e32 v4, v2
	s_waitcnt vmcnt(0)
	v_readfirstlane_b32 s6, v3
	v_sub_u32_e32 v3, 0, v2
	v_rcp_iflag_f32_e32 v4, v4
	v_add_u32_e32 v5, s6, v1
	v_mul_f32_e32 v4, 0x4f7ffffe, v4
	v_cvt_u32_f32_e32 v4, v4
	v_mul_lo_u32 v1, v3, v4
	v_mul_hi_u32 v1, v4, v1
	v_add_u32_e32 v1, v4, v1
	v_mul_hi_u32 v1, v5, v1
	v_mul_lo_u32 v3, v1, v2
	v_sub_u32_e32 v3, v5, v3
	v_add_u32_e32 v4, 1, v1
	v_cmp_ge_u32_e32 vcc, v3, v2
	s_nop 1
	v_cndmask_b32_e32 v1, v1, v4, vcc
	v_sub_u32_e32 v4, v3, v2
	v_cndmask_b32_e32 v3, v3, v4, vcc
	v_add_u32_e32 v4, 1, v1
	v_cmp_ge_u32_e32 vcc, v3, v2
	v_add_u32_e32 v3, 1, v5
	s_nop 0
	v_cndmask_b32_e32 v1, v1, v4, vcc
	v_mul_lo_u32 v4, v2, v1
	v_add_u32_e32 v2, v4, v2
	v_cmp_ne_u32_e32 vcc, v3, v2
	s_and_saveexec_b64 s[6:7], vcc
	s_xor_b64 s[6:7], exec, s[6:7]
	s_cbranch_execz .LBB0_855
	buffer_inv sc1
	s_waitcnt lgkmcnt(0)
	v_mov_b32_e32 v0, 0x2000
	global_load_dword v0, v0, s[4:5] offset:1024 sc1
	s_add_u32 s18, s4, 0x2400
	s_addc_u32 s19, s5, 0
	s_waitcnt vmcnt(0)
	v_cmp_eq_u32_e32 vcc, v0, v1
	s_and_saveexec_b64 s[8:9], vcc
	s_cbranch_execz .LBB0_854
	s_add_u32 s16, s72, 0x1fd00200
	s_addc_u32 s17, s73, 0
	s_mov_b32 s11, 1
	s_mov_b64 s[20:21], 0
	v_mov_b32_e32 v0, 0
	s_branch .LBB0_845

.LBB0_934:
	s_or_b64 exec, exec, s[8:9]
	v_cvt_f32_u32_e32 v4, v2
	s_waitcnt vmcnt(0)
	v_readfirstlane_b32 s6, v3
	v_sub_u32_e32 v3, 0, v2
	v_rcp_iflag_f32_e32 v4, v4
	v_add_u32_e32 v5, s6, v1
	v_mul_f32_e32 v4, 0x4f7ffffe, v4
	v_cvt_u32_f32_e32 v4, v4
	v_mul_lo_u32 v1, v3, v4
	v_mul_hi_u32 v1, v4, v1
	v_add_u32_e32 v1, v4, v1
	v_mul_hi_u32 v1, v5, v1
	v_mul_lo_u32 v3, v1, v2
	v_sub_u32_e32 v3, v5, v3
	v_add_u32_e32 v4, 1, v1
	v_cmp_ge_u32_e32 vcc, v3, v2
	s_nop 1
	v_cndmask_b32_e32 v1, v1, v4, vcc
	v_sub_u32_e32 v4, v3, v2
	v_cndmask_b32_e32 v3, v3, v4, vcc
	v_add_u32_e32 v4, 1, v1
	v_cmp_ge_u32_e32 vcc, v3, v2
	v_add_u32_e32 v3, 1, v5
	s_nop 0
	v_cndmask_b32_e32 v1, v1, v4, vcc
	v_mul_lo_u32 v4, v2, v1
	v_add_u32_e32 v2, v4, v2
	v_cmp_ne_u32_e32 vcc, v3, v2
	s_and_saveexec_b64 s[6:7], vcc
	s_xor_b64 s[6:7], exec, s[6:7]
	s_cbranch_execz .LBB0_948
	buffer_inv sc1
	s_waitcnt lgkmcnt(0)
	v_mov_b32_e32 v0, 0x2000
	global_load_dword v0, v0, s[4:5] offset:1024 sc1
	s_add_u32 s20, s4, 0x2400
	s_addc_u32 s21, s5, 0
	s_waitcnt vmcnt(0)
	v_cmp_eq_u32_e32 vcc, v0, v1
	s_and_saveexec_b64 s[8:9], vcc
	s_cbranch_execz .LBB0_947
	s_add_u32 s18, s72, 0x1fd00200
	s_addc_u32 s19, s73, 0
	s_mov_b32 s11, 1
	s_mov_b64 s[22:23], 0
	v_mov_b32_e32 v0, 0
	s_branch .LBB0_938

.LBB0_1022:
	s_or_b64 exec, exec, s[8:9]
	v_cvt_f32_u32_e32 v4, v2
	s_waitcnt vmcnt(0)
	v_readfirstlane_b32 s6, v3
	v_sub_u32_e32 v3, 0, v2
	v_rcp_iflag_f32_e32 v4, v4
	v_add_u32_e32 v5, s6, v1
	v_mul_f32_e32 v4, 0x4f7ffffe, v4
	v_cvt_u32_f32_e32 v4, v4
	v_mul_lo_u32 v1, v3, v4
	v_mul_hi_u32 v1, v4, v1
	v_add_u32_e32 v1, v4, v1
	v_mul_hi_u32 v1, v5, v1
	v_mul_lo_u32 v3, v1, v2
	v_sub_u32_e32 v3, v5, v3
	v_add_u32_e32 v4, 1, v1
	v_cmp_ge_u32_e32 vcc, v3, v2
	s_nop 1
	v_cndmask_b32_e32 v1, v1, v4, vcc
	v_sub_u32_e32 v4, v3, v2
	v_cndmask_b32_e32 v3, v3, v4, vcc
	v_add_u32_e32 v4, 1, v1
	v_cmp_ge_u32_e32 vcc, v3, v2
	v_add_u32_e32 v3, 1, v5
	s_nop 0
	v_cndmask_b32_e32 v1, v1, v4, vcc
	v_mul_lo_u32 v4, v2, v1
	v_add_u32_e32 v2, v4, v2
	v_cmp_ne_u32_e32 vcc, v3, v2
	s_and_saveexec_b64 s[6:7], vcc
	s_xor_b64 s[6:7], exec, s[6:7]
	s_cbranch_execz .LBB0_1036
	buffer_inv sc1
	s_waitcnt lgkmcnt(0)
	v_mov_b32_e32 v0, 0x2000
	global_load_dword v0, v0, s[4:5] offset:1024 sc1
	s_add_u32 s22, s4, 0x2400
	s_addc_u32 s23, s5, 0
	s_waitcnt vmcnt(0)
	v_cmp_eq_u32_e32 vcc, v0, v1
	s_and_saveexec_b64 s[8:9], vcc
	s_cbranch_execz .LBB0_1035
	s_add_u32 s20, s72, 0x1fd00200
	s_addc_u32 s21, s73, 0
	s_mov_b32 s11, 1
	s_mov_b64 s[28:29], 0
	v_mov_b32_e32 v0, 0
	s_branch .LBB0_1026

.LBB0_1081:
	s_or_b64 exec, exec, s[6:7]
	v_cvt_f32_u32_e32 v4, v2
	s_waitcnt vmcnt(0)
	v_readfirstlane_b32 s4, v3
	v_sub_u32_e32 v3, 0, v2
	v_rcp_iflag_f32_e32 v4, v4
	v_add_u32_e32 v5, s4, v1
	v_mul_f32_e32 v4, 0x4f7ffffe, v4
	v_cvt_u32_f32_e32 v4, v4
	v_mul_lo_u32 v1, v3, v4
	v_mul_hi_u32 v1, v4, v1
	v_add_u32_e32 v1, v4, v1
	v_mul_hi_u32 v1, v5, v1
	v_mul_lo_u32 v3, v1, v2
	v_sub_u32_e32 v3, v5, v3
	v_add_u32_e32 v4, 1, v1
	v_cmp_ge_u32_e32 vcc, v3, v2
	s_nop 1
	v_cndmask_b32_e32 v1, v1, v4, vcc
	v_sub_u32_e32 v4, v3, v2
	v_cndmask_b32_e32 v3, v3, v4, vcc
	v_add_u32_e32 v4, 1, v1
	v_cmp_ge_u32_e32 vcc, v3, v2
	v_add_u32_e32 v3, 1, v5
	s_nop 0
	v_cndmask_b32_e32 v1, v1, v4, vcc
	v_mul_lo_u32 v4, v2, v1
	v_add_u32_e32 v2, v4, v2
	v_cmp_ne_u32_e32 vcc, v3, v2
	s_and_saveexec_b64 s[4:5], vcc
	s_xor_b64 s[4:5], exec, s[4:5]
	s_cbranch_execz .LBB0_1095
	buffer_inv sc1
	s_waitcnt lgkmcnt(0)
	v_mov_b32_e32 v0, 0x2000
	global_load_dword v0, v0, s[2:3] offset:1024 sc1
	s_add_u32 s20, s2, 0x2400
	s_addc_u32 s21, s3, 0
	s_waitcnt vmcnt(0)
	v_cmp_eq_u32_e32 vcc, v0, v1
	s_and_saveexec_b64 s[6:7], vcc
	s_cbranch_execz .LBB0_1094
	s_add_u32 s8, s72, 0x1fd00200
	s_addc_u32 s9, s73, 0
	s_mov_b32 s11, 1
	s_mov_b64 s[22:23], 0
	v_mov_b32_e32 v0, 0
	s_branch .LBB0_1085

.LBB0_1094:
	s_or_b64 exec, exec, s[6:7]
	s_waitcnt vmcnt(0)
	s_nop 0
	s_waitcnt vmcnt(0)

.LBB0_1206:
	s_or_b64 exec, exec, s[8:9]
	v_cvt_f32_u32_e32 v4, v2
	s_waitcnt vmcnt(0)
	v_readfirstlane_b32 s6, v3
	v_sub_u32_e32 v3, 0, v2
	v_rcp_iflag_f32_e32 v4, v4
	v_add_u32_e32 v5, s6, v1
	v_mul_f32_e32 v4, 0x4f7ffffe, v4
	v_cvt_u32_f32_e32 v4, v4
	v_mul_lo_u32 v1, v3, v4
	v_mul_hi_u32 v1, v4, v1
	v_add_u32_e32 v1, v4, v1
	v_mul_hi_u32 v1, v5, v1
	v_mul_lo_u32 v3, v1, v2
	v_sub_u32_e32 v3, v5, v3
	v_add_u32_e32 v4, 1, v1
	v_cmp_ge_u32_e32 vcc, v3, v2
	s_nop 1
	v_cndmask_b32_e32 v1, v1, v4, vcc
	v_sub_u32_e32 v4, v3, v2
	v_cndmask_b32_e32 v3, v3, v4, vcc
	v_add_u32_e32 v4, 1, v1
	v_cmp_ge_u32_e32 vcc, v3, v2
	v_add_u32_e32 v3, 1, v5
	s_nop 0
	v_cndmask_b32_e32 v1, v1, v4, vcc
	v_mul_lo_u32 v4, v2, v1
	v_add_u32_e32 v2, v4, v2
	v_cmp_ne_u32_e32 vcc, v3, v2
	s_and_saveexec_b64 s[6:7], vcc
	s_xor_b64 s[6:7], exec, s[6:7]
	s_cbranch_execz .LBB0_1220
	buffer_inv sc1
	s_waitcnt lgkmcnt(0)
	v_mov_b32_e32 v0, 0x2000
	global_load_dword v0, v0, s[4:5] offset:1024 sc1
	s_add_u32 s22, s4, 0x2400
	s_addc_u32 s23, s5, 0
	s_waitcnt vmcnt(0)
	v_cmp_eq_u32_e32 vcc, v0, v1
	s_and_saveexec_b64 s[8:9], vcc
	s_cbranch_execz .LBB0_1219
	s_add_u32 s20, s72, 0x1fd00200
	s_addc_u32 s21, s73, 0
	s_mov_b32 s11, 1
	s_mov_b64 s[24:25], 0
	v_mov_b32_e32 v0, 0
	s_branch .LBB0_1210

.LBB0_1303:
	s_or_b64 exec, exec, s[8:9]
	v_cvt_f32_u32_e32 v4, v2
	s_waitcnt vmcnt(0)
	v_readfirstlane_b32 s6, v3
	v_sub_u32_e32 v3, 0, v2
	v_rcp_iflag_f32_e32 v4, v4
	v_add_u32_e32 v5, s6, v1
	v_mul_f32_e32 v4, 0x4f7ffffe, v4
	v_cvt_u32_f32_e32 v4, v4
	v_mul_lo_u32 v1, v3, v4
	v_mul_hi_u32 v1, v4, v1
	v_add_u32_e32 v1, v4, v1
	v_mul_hi_u32 v1, v5, v1
	v_mul_lo_u32 v3, v1, v2
	v_sub_u32_e32 v3, v5, v3
	v_add_u32_e32 v4, 1, v1
	v_cmp_ge_u32_e32 vcc, v3, v2
	s_nop 1
	v_cndmask_b32_e32 v1, v1, v4, vcc
	v_sub_u32_e32 v4, v3, v2
	v_cndmask_b32_e32 v3, v3, v4, vcc
	v_add_u32_e32 v4, 1, v1
	v_cmp_ge_u32_e32 vcc, v3, v2
	v_add_u32_e32 v3, 1, v5
	s_nop 0
	v_cndmask_b32_e32 v1, v1, v4, vcc
	v_mul_lo_u32 v4, v2, v1
	v_add_u32_e32 v2, v4, v2
	v_cmp_ne_u32_e32 vcc, v3, v2
	s_and_saveexec_b64 s[6:7], vcc
	s_xor_b64 s[6:7], exec, s[6:7]
	s_cbranch_execz .LBB0_1317
	buffer_inv sc1
	s_waitcnt lgkmcnt(0)
	v_mov_b32_e32 v0, 0x2000
	global_load_dword v0, v0, s[4:5] offset:1024 sc1
	s_add_u32 s12, s4, 0x2400
	s_addc_u32 s13, s5, 0
	s_waitcnt vmcnt(0)
	v_cmp_eq_u32_e32 vcc, v0, v1
	s_and_saveexec_b64 s[8:9], vcc
	s_cbranch_execz .LBB0_1316
	s_add_u32 s10, s72, 0x1fd00200
	s_addc_u32 s11, s73, 0
	s_mov_b32 s24, 1
	s_mov_b64 s[14:15], 0
	v_mov_b32_e32 v0, 0
	s_branch .LBB0_1307
